# also nt on read-once loads of combine_rows (P6) and the ffn2 conv_mat loops (P8)
# baseline (speedup 1.0000x reference)
; __device__ __forceinline__ void combine_rows(const bf16* O1, const bf16* O2, const bf16* OR_, const bf16* Gs, bf16* YA, bf16* YR, float lam, const float* subln, const float* gnorm, int gw, int NGW, int lane) {
;     ...
;     for (int m = gw; m < M; m += NGW) { const size_t p = (size_t)m * 1024 + 16 * lane;
;         float a[16], b2[16], r[16], g[16]; unpack16(O1 + p, a); unpack16(O2 + p, b2); unpack16(OR_ + p, r); unpack16(Gs + p, g);
;         float sa = 0.f, sr = 0.f;
; #pragma unroll
;         for (int i = 0; i < 16; ++i) { a[i] = a[i] - lam * b2[i]; sa += a[i] * a[i]; sr += r[i] * r[i]; }
;         sa += __shfl_xor(sa, 1); sa += __shfl_xor(sa, 2); sa += __shfl_xor(sa, 4); sr += __shfl_xor(sr, 1); sr += __shfl_xor(sr, 2); sr += __shfl_xor(sr, 4);
;         const float ra = 1.0f / sqrtf(sa * (1.f / 128.f) + EPS), rr = 1.0f / sqrtf(sr * (1.f / 128.f) + EPS);
; #pragma unroll
;         for (int i = 0; i < 16; ++i) { a[i] = a[i] * ra * wa[i]; r[i] = r[i] * rr * wg[i] * g[i]; }
;         pack16(YA + p, a); pack16(YR + p, r); }
.LBB0_1608:
	v_add_co_u32_e32 v50, vcc, 0xfc000000, v24
	global_load_dwordx4 v[20:23], v[24:25], off nt
	global_load_dwordx4 v[16:19], v[24:25], off offset:-16 nt
	v_addc_co_u32_e32 v51, vcc, -1, v25, vcc
	v_add_co_u32_e32 v68, vcc, s3, v24
	v_lshl_add_u64 v[48:49], v[24:25], 0, s[0:1]
	v_lshl_add_u64 v[46:47], v[24:25], 0, s[4:5]
	v_addc_co_u32_e32 v69, vcc, -1, v25, vcc
	global_load_dwordx4 v[60:63], v[48:49], off offset:16 nt
	s_nop 0
	global_load_dwordx4 v[48:51], v[50:51], off offset:-16 nt
	s_nop 0
	global_load_dwordx4 v[64:67], v[46:47], off offset:16 nt
	s_nop 0
	global_load_dwordx4 v[68:71], v[68:69], off offset:-16 nt
	v_add_co_u32_e32 v72, vcc, s18, v24
	v_lshl_add_u64 v[44:45], v[24:25], 0, s[14:15]
	s_nop 0
	v_addc_co_u32_e32 v73, vcc, -1, v25, vcc
	global_load_dwordx4 v[44:47], v[44:45], off offset:16 nt
	s_nop 0
	global_load_dwordx4 v[72:75], v[72:73], off offset:-16 nt
	v_add_co_u32_e64 v52, s[10:11], s20, v24
	s_add_i32 s22, s22, s64
	s_nop 0
	v_addc_co_u32_e64 v53, s[10:11], -1, v25, s[10:11]
	s_cmpk_lt_i32 s22, 0x4000
	s_waitcnt vmcnt(7)
	v_and_b32_e32 v76, 0xffff0000, v23
	s_waitcnt vmcnt(6)
	v_lshlrev_b32_e32 v84, 16, v16
	v_and_b32_e32 v85, 0xffff0000, v16
	v_lshlrev_b32_e32 v77, 16, v23
	v_lshlrev_b32_e32 v78, 16, v22
	v_and_b32_e32 v79, 0xffff0000, v22
	v_lshlrev_b32_e32 v22, 16, v21
	v_and_b32_e32 v23, 0xffff0000, v21
	v_lshlrev_b32_e32 v80, 16, v20
	v_and_b32_e32 v81, 0xffff0000, v20
	v_lshlrev_b32_e32 v20, 16, v19
	v_and_b32_e32 v21, 0xffff0000, v19
	v_lshlrev_b32_e32 v82, 16, v18
	v_and_b32_e32 v83, 0xffff0000, v18
	v_lshlrev_b32_e32 v18, 16, v17
	v_and_b32_e32 v19, 0xffff0000, v17
	v_pk_mul_f32 v[98:99], v[84:85], v[84:85]
	v_pk_mul_f32 v[96:97], v[18:19], v[18:19]
	v_add_f32_e32 v59, v98, v99
	s_waitcnt vmcnt(5)
	v_and_b32_e32 v100, 0xffff0000, v63
	v_lshlrev_b32_e32 v101, 16, v63
	v_lshlrev_b32_e32 v102, 16, v62
	v_and_b32_e32 v103, 0xffff0000, v62
	v_lshlrev_b32_e32 v62, 16, v61
	v_and_b32_e32 v63, 0xffff0000, v61
	v_lshlrev_b32_e32 v104, 16, v60
	v_and_b32_e32 v105, 0xffff0000, v60
	s_waitcnt vmcnt(4)
	v_lshlrev_b32_e32 v60, 16, v51
	v_and_b32_e32 v61, 0xffff0000, v51
	v_lshlrev_b32_e32 v106, 16, v50
	v_and_b32_e32 v107, 0xffff0000, v50
	v_lshlrev_b32_e32 v50, 16, v49
	v_and_b32_e32 v51, 0xffff0000, v49
	v_lshlrev_b32_e32 v108, 16, v48
	v_and_b32_e32 v109, 0xffff0000, v48
	s_waitcnt vmcnt(3)
	v_and_b32_e32 v48, 0xffff0000, v67
	v_lshlrev_b32_e32 v49, 16, v67
	v_lshlrev_b32_e32 v98, 16, v66
	v_and_b32_e32 v99, 0xffff0000, v66
	v_lshlrev_b32_e32 v66, 16, v65
	v_and_b32_e32 v67, 0xffff0000, v65
	v_lshlrev_b32_e32 v110, 16, v64
	v_and_b32_e32 v111, 0xffff0000, v64
	s_waitcnt vmcnt(2)
	v_lshlrev_b32_e32 v64, 16, v71
	v_and_b32_e32 v65, 0xffff0000, v71
	v_lshlrev_b32_e32 v112, 16, v70
	v_and_b32_e32 v113, 0xffff0000, v70
	v_lshlrev_b32_e32 v70, 16, v69
	v_and_b32_e32 v71, 0xffff0000, v69
	v_lshlrev_b32_e32 v114, 16, v68
	v_and_b32_e32 v115, 0xffff0000, v68
	v_add_f32_e32 v59, v96, v59
	v_pk_mul_f32 v[94:95], v[82:83], v[82:83]
	v_pk_fma_f32 v[50:51], v[26:27], v[70:71], v[50:51] neg_lo:[1,0,0] neg_hi:[1,0,0]
	v_pk_fma_f32 v[70:71], v[26:27], v[114:115], v[108:109] neg_lo:[1,0,0] neg_hi:[1,0,0]
	v_add_f32_e32 v59, v97, v59
	v_pk_mul_f32 v[118:119], v[70:71], v[70:71]
	v_add_f32_e32 v59, v94, v59
	v_pk_mul_f32 v[92:93], v[20:21], v[20:21]
	v_pk_mul_f32 v[116:117], v[50:51], v[50:51]
	v_add_f32_e32 v94, v118, v119
	v_add_f32_e32 v59, v95, v59
	v_pk_fma_f32 v[60:61], v[26:27], v[64:65], v[60:61] neg_lo:[1,0,0] neg_hi:[1,0,0]
	v_pk_fma_f32 v[64:65], v[26:27], v[112:113], v[106:107] neg_lo:[1,0,0] neg_hi:[1,0,0]
	v_add_f32_e32 v94, v116, v94
	v_add_f32_e32 v59, v92, v59
	v_pk_mul_f32 v[90:91], v[80:81], v[80:81]
	v_pk_mul_f32 v[114:115], v[64:65], v[64:65]
	v_add_f32_e32 v92, v117, v94
	v_add_f32_e32 v59, v93, v59
	v_add_f32_e32 v92, v114, v92
	v_add_f32_e32 v59, v90, v59
	v_pk_mul_f32 v[88:89], v[22:23], v[22:23]
	v_pk_mul_f32 v[112:113], v[60:61], v[60:61]
	v_add_f32_e32 v90, v115, v92
	v_add_f32_e32 v59, v91, v59
	v_pk_fma_f32 v[62:63], v[26:27], v[66:67], v[62:63] neg_lo:[1,0,0] neg_hi:[1,0,0]
	v_pk_fma_f32 v[66:67], v[26:27], v[110:111], v[104:105] neg_lo:[1,0,0] neg_hi:[1,0,0]
	v_add_f32_e32 v90, v112, v90
	v_add_f32_e32 v59, v88, v59
	v_pk_mul_f32 v[86:87], v[78:79], v[78:79]
	v_pk_mul_f32 v[110:111], v[66:67], v[66:67]
	v_add_f32_e32 v88, v113, v90
	v_add_f32_e32 v59, v89, v59
	v_add_f32_e32 v88, v110, v88
	v_add_f32_e32 v59, v86, v59
	v_pk_mul_f32 v[16:17], v[76:77], v[76:77]
	v_pk_mul_f32 v[108:109], v[62:63], v[62:63]
	v_add_f32_e32 v86, v111, v88
	v_add_f32_e32 v59, v87, v59
	v_pk_fma_f32 v[68:69], v[26:27], v[98:99], v[102:103] neg_lo:[1,0,0] neg_hi:[1,0,0]
	v_add_f32_e32 v86, v108, v86
	v_add_f32_e32 v17, v17, v59
	v_pk_mul_f32 v[96:97], v[68:69], v[68:69]
	v_add_f32_e32 v59, v109, v86
	v_add_f32_e32 v16, v16, v17
	v_pk_fma_f32 v[48:49], v[26:27], v[48:49], v[100:101] neg_lo:[1,0,0] neg_hi:[1,0,0]
	v_add_f32_e32 v17, v96, v59
	ds_bpermute_b32 v59, v54, v16
	s_waitcnt vmcnt(1)
	v_lshlrev_b32_e32 v100, 16, v45
	v_and_b32_e32 v101, 0xffff0000, v45
	v_lshlrev_b32_e32 v102, 16, v44
	v_and_b32_e32 v103, 0xffff0000, v44
	s_waitcnt vmcnt(0)
	v_lshlrev_b32_e32 v44, 16, v75
	v_and_b32_e32 v45, 0xffff0000, v75
	v_lshlrev_b32_e32 v104, 16, v74
	v_and_b32_e32 v105, 0xffff0000, v74
	v_lshlrev_b32_e32 v74, 16, v73
	v_and_b32_e32 v75, 0xffff0000, v73
	v_lshlrev_b32_e32 v106, 16, v72
	v_and_b32_e32 v107, 0xffff0000, v72
	v_pk_mul_f32 v[72:73], v[48:49], v[48:49]
	v_add_f32_e32 v17, v97, v17
	v_add_f32_e32 v17, v73, v17
	v_add_f32_e32 v17, v72, v17
	ds_bpermute_b32 v72, v54, v17
	s_waitcnt lgkmcnt(1)
; __device__ __forceinline__ void combine_rows(const bf16* O1, const bf16* O2, const bf16* OR_, const bf16* Gs, bf16* YA, bf16* YR, float lam, const float* subln, const float* gnorm, int gw, int NGW, int lane) {
;     ...
;         for (int i = 0; i < 16; ++i) { a[i] = a[i] - lam * b2[i]; sa += a[i] * a[i]; sr += r[i] * r[i]; }
;         sa += __shfl_xor(sa, 1); sa += __shfl_xor(sa, 2); sa += __shfl_xor(sa, 4); sr += __shfl_xor(sr, 1); sr += __shfl_xor(sr, 2); sr += __shfl_xor(sr, 4);
;         const float ra = 1.0f / sqrtf(sa * (1.f / 128.f) + EPS), rr = 1.0f / sqrtf(sr * (1.f / 128.f) + EPS);
; #pragma unroll
;         for (int i = 0; i < 16; ++i) { a[i] = a[i] * ra * wa[i]; r[i] = r[i] * rr * wg[i] * g[i]; }
;         pack16(YA + p, a); pack16(YR + p, r); }
	v_add_f32_e32 v16, v16, v59
	ds_bpermute_b32 v59, v55, v16
	v_lshlrev_b32_e32 v98, 16, v46
	v_and_b32_e32 v99, 0xffff0000, v46
	s_waitcnt lgkmcnt(1)
	v_add_f32_e32 v17, v17, v72
	ds_bpermute_b32 v72, v55, v17
	s_waitcnt lgkmcnt(1)
	v_add_f32_e32 v16, v16, v59
	ds_bpermute_b32 v59, v56, v16
	v_lshlrev_b32_e32 v46, 16, v47
	v_and_b32_e32 v47, 0xffff0000, v47
	s_waitcnt lgkmcnt(1)
	v_add_f32_e32 v17, v17, v72
	ds_bpermute_b32 v72, v56, v17
	s_waitcnt lgkmcnt(1)
	v_add_f32_e32 v16, v16, v59
	v_fmamk_f32 v16, v16, 0x3c000000, v57
	v_mul_f32_e32 v59, 0x4f800000, v16
	v_cmp_gt_f32_e32 vcc, s19, v16
	s_waitcnt lgkmcnt(0)
	v_add_f32_e32 v17, v17, v72
	v_fmamk_f32 v17, v17, 0x3c000000, v57
	v_cndmask_b32_e32 v16, v16, v59, vcc
	v_sqrt_f32_e32 v59, v16
	v_mul_f32_e32 v72, 0x4f800000, v17
	v_cmp_gt_f32_e64 s[10:11], s19, v17
	v_add_u32_e32 v73, -1, v59
	s_nop 0
	v_cndmask_b32_e64 v17, v17, v72, s[10:11]
	v_sqrt_f32_e32 v72, v17
	v_add_u32_e32 v86, 1, v59
	v_fma_f32 v87, -v73, v59, v16
	v_fma_f32 v88, -v86, v59, v16
	v_cmp_ge_f32_e64 s[12:13], 0, v87
	s_nop 1
	v_cndmask_b32_e64 v59, v59, v73, s[12:13]
	v_cmp_lt_f32_e64 s[12:13], 0, v88
	v_add_u32_e32 v73, -1, v72
	v_fma_f32 v88, -v73, v72, v17
	v_cndmask_b32_e64 v59, v59, v86, s[12:13]
	v_add_u32_e32 v86, 1, v72
	v_mul_f32_e32 v87, 0x37800000, v59
	v_fma_f32 v89, -v86, v72, v17
	v_cndmask_b32_e32 v59, v59, v87, vcc
	v_cmp_class_f32_e32 vcc, v16, v58
	v_cmp_ge_f32_e64 s[12:13], 0, v88
	s_nop 0
	v_cndmask_b32_e32 v59, v59, v16, vcc
	v_cndmask_b32_e64 v72, v72, v73, s[12:13]
	v_cmp_lt_f32_e32 vcc, 0, v89
	s_nop 1
	v_cndmask_b32_e32 v16, v72, v86, vcc
	v_div_scale_f32 v72, s[12:13], v59, v59, 1.0
	v_mul_f32_e32 v86, 0x37800000, v16
	v_rcp_f32_e32 v87, v72
	v_cndmask_b32_e64 v16, v16, v86, s[10:11]
	v_cmp_class_f32_e32 vcc, v17, v58
	v_div_scale_f32 v73, s[12:13], 1.0, v59, 1.0
	s_nop 0
	v_cndmask_b32_e32 v16, v16, v17, vcc
	v_div_scale_f32 v17, s[10:11], v16, v16, 1.0
	v_rcp_f32_e32 v88, v17
	v_fma_f32 v89, -v72, v87, 1.0
	v_fmac_f32_e32 v87, v89, v87
	v_mul_f32_e32 v89, v73, v87
	v_fma_f32 v90, -v72, v89, v73
	v_fma_f32 v91, -v17, v88, 1.0
	v_div_scale_f32 v86, vcc, 1.0, v16, 1.0
	v_fmac_f32_e32 v89, v90, v87
	v_fmac_f32_e32 v88, v91, v88
	v_fma_f32 v72, -v72, v89, v73
	v_mul_f32_e32 v73, v86, v88
	v_fma_f32 v90, -v17, v73, v86
	v_fmac_f32_e32 v73, v90, v88
	v_fma_f32 v17, -v17, v73, v86
	v_div_fmas_f32 v17, v17, v88, v73
	s_mov_b64 vcc, s[12:13]
	v_div_fixup_f32 v16, v17, v16, 1.0
	v_div_fmas_f32 v17, v72, v87, v89
	v_pk_mul_f32 v[70:71], v[70:71], v[16:17] op_sel_hi:[1,0]
	v_div_fixup_f32 v86, v17, v59, 1.0
	v_pk_mul_f32 v[50:51], v[50:51], v[16:17] op_sel_hi:[1,0]
	v_pk_mul_f32 v[64:65], v[64:65], v[16:17] op_sel_hi:[1,0]
	v_pk_mul_f32 v[60:61], v[60:61], v[16:17] op_sel_hi:[1,0]
	v_pk_mul_f32 v[66:67], v[66:67], v[16:17] op_sel_hi:[1,0]
	v_pk_mul_f32 v[62:63], v[62:63], v[16:17] op_sel_hi:[1,0]
	v_pk_mul_f32 v[68:69], v[68:69], v[16:17] op_sel_hi:[1,0]
	v_pk_mul_f32 v[16:17], v[48:49], v[16:17] op_sel_hi:[1,0]
	v_pk_mul_f32 v[48:49], v[28:29], v[70:71]
	v_pk_mul_f32 v[70:71], v[86:87], v[84:85] op_sel_hi:[0,1]
	v_pk_mul_f32 v[18:19], v[86:87], v[18:19] op_sel_hi:[0,1]
	v_pk_mul_f32 v[82:83], v[86:87], v[82:83] op_sel_hi:[0,1]
	v_pk_mul_f32 v[20:21], v[86:87], v[20:21] op_sel_hi:[0,1]
	v_pk_mul_f32 v[50:51], v[30:31], v[50:51]
	v_pk_mul_f32 v[64:65], v[32:33], v[64:65]
	v_pk_mul_f32 v[60:61], v[34:35], v[60:61]
	v_pk_mul_f32 v[80:81], v[86:87], v[80:81] op_sel_hi:[0,1]
	v_pk_mul_f32 v[22:23], v[86:87], v[22:23] op_sel_hi:[0,1]
	v_pk_mul_f32 v[78:79], v[86:87], v[78:79] op_sel_hi:[0,1]
	v_pk_mul_f32 v[84:85], v[42:43], v[16:17] op_sel:[0,1] op_sel_hi:[1,0]
	v_pk_mul_f32 v[16:17], v[86:87], v[76:77] op_sel_hi:[0,1]
	v_pk_mul_f32 v[70:71], v[12:13], v[70:71]
	v_pk_mul_f32 v[76:77], v[14:15], v[18:19]
	v_pk_mul_f32 v[82:83], v[8:9], v[82:83]
	v_pk_mul_f32 v[86:87], v[10:11], v[20:21]
	v_add_co_u32_e32 v72, vcc, s21, v24
	v_pk_mul_f32 v[66:67], v[36:37], v[66:67]
	v_pk_mul_f32 v[62:63], v[38:39], v[62:63]
	v_pk_mul_f32 v[68:69], v[40:41], v[68:69]
	v_pk_mul_f32 v[80:81], v[4:5], v[80:81]
	v_pk_mul_f32 v[88:89], v[6:7], v[22:23]
	v_pk_mul_f32 v[78:79], v[0:1], v[78:79]
	v_pk_mul_f32 v[90:91], v[2:3], v[16:17] op_sel:[0,1] op_sel_hi:[1,0]
	v_cvt_pk_bf16_f32 v16, v48, v49
	v_cvt_pk_bf16_f32 v17, v50, v51
	v_cvt_pk_bf16_f32 v18, v64, v65
	v_cvt_pk_bf16_f32 v19, v60, v61
	v_pk_mul_f32 v[48:49], v[70:71], v[106:107]
	v_pk_mul_f32 v[50:51], v[76:77], v[74:75]
	v_pk_mul_f32 v[60:61], v[82:83], v[104:105]
	v_pk_mul_f32 v[44:45], v[86:87], v[44:45]
	v_addc_co_u32_e32 v73, vcc, -1, v25, vcc
	v_lshl_add_u64 v[24:25], v[24:25], 0, s[16:17]
	v_cvt_pk_bf16_f32 v20, v66, v67
	v_cvt_pk_bf16_f32 v21, v62, v63
	v_cvt_pk_bf16_f32 v22, v68, v69
	v_cvt_pk_bf16_f32 v23, v84, v85
	v_pk_mul_f32 v[62:63], v[80:81], v[102:103]
	v_pk_mul_f32 v[64:65], v[88:89], v[100:101]
	v_pk_mul_f32 v[66:67], v[78:79], v[98:99]
	v_pk_mul_f32 v[46:47], v[90:91], v[46:47]
	global_store_dwordx4 v[52:53], v[16:19], off offset:-16
	global_store_dwordx4 v[52:53], v[20:23], off
	s_nop 0
	v_cvt_pk_bf16_f32 v16, v48, v49
	v_cvt_pk_bf16_f32 v17, v50, v51
	v_cvt_pk_bf16_f32 v18, v60, v61
	v_cvt_pk_bf16_f32 v19, v44, v45
	v_cvt_pk_bf16_f32 v20, v62, v63
	v_cvt_pk_bf16_f32 v21, v64, v65
	v_cvt_pk_bf16_f32 v22, v66, v67
	v_cvt_pk_bf16_f32 v23, v46, v47
	global_store_dwordx4 v[72:73], v[16:19], off offset:-16
	global_store_dwordx4 v[72:73], v[20:23], off
	s_cbranch_scc1 .LBB0_1608

; #define LAS __attribute__((address_space(3)))
; __device__ __forceinline__ void tr_item(const float* W, const float* nw, int K, int N, bf16* WT, int k0, int n0, int drow0, LAS float* scr, int lane) {
;     { const int r = lane >> 3, c4 = lane & 7; f32x4 v[8];
; #pragma unroll
;       for (int i = 0; i < 8; ++i) v[i] = *(const f32x4*)(W + (size_t)(k0 + 8 * i + r) * N + n0 + 4 * c4);
; #pragma unroll
;       for (int i = 0; i < 8; ++i) { LAS float* d = scr + (8 * i + r) * 33 + 4 * c4; const float s = nw ? nw[k0 + 8 * i + r] : 1.f; d[0] = v[i].x * s; d[1] = v[i].y * s; d[2] = v[i].z * s; d[3] = v[i].w * s; } }
.LBB0_1768:
	s_lshl_b32 s0, s11, 6
	v_or_b32_e32 v36, s0, v224
	s_ashr_i32 s11, s10, 31
	v_lshl_add_u64 v[0:1], s[10:11], 2, v[32:33]
	v_or_b32_e32 v4, 8, v36
	v_mad_i64_i32 v[2:3], s[10:11], v36, s15, v[0:1]
	v_mad_i64_i32 v[4:5], s[10:11], v4, s15, v[0:1]
	global_load_dwordx4 v[28:31], v[2:3], off nt
	global_load_dwordx4 v[24:27], v[4:5], off nt
	v_or_b32_e32 v2, 16, v36
	v_or_b32_e32 v4, 24, v36
	v_mad_i64_i32 v[2:3], s[10:11], v2, s15, v[0:1]
	v_mad_i64_i32 v[4:5], s[10:11], v4, s15, v[0:1]
	global_load_dwordx4 v[20:23], v[2:3], off nt
	global_load_dwordx4 v[16:19], v[4:5], off nt
	v_or_b32_e32 v2, 32, v36
	v_or_b32_e32 v4, 40, v36
	v_mad_i64_i32 v[2:3], s[10:11], v2, s15, v[0:1]
	v_mad_i64_i32 v[4:5], s[10:11], v4, s15, v[0:1]
	global_load_dwordx4 v[12:15], v[2:3], off nt
	global_load_dwordx4 v[8:11], v[4:5], off nt
	v_or_b32_e32 v2, 48, v36
	v_or_b32_e32 v4, 56, v36
	v_mad_i64_i32 v[2:3], s[10:11], v2, s15, v[0:1]
	v_mad_i64_i32 v[0:1], s[10:11], v4, s15, v[0:1]
	global_load_dwordx4 v[4:7], v[2:3], off nt
	s_nop 0
	global_load_dwordx4 v[0:3], v[0:1], off nt
	v_ashrrev_i32_e32 v37, 31, v36
	v_lshl_add_u64 v[36:37], v[36:37], 2, s[84:85]
	global_load_dword v245, v[36:37], off
	global_load_dword v246, v[36:37], off offset:32
	global_load_dword v247, v[36:37], off offset:64
	global_load_dword v248, v[36:37], off offset:96
	global_load_dword v249, v[36:37], off offset:128
	global_load_dword v251, v[36:37], off offset:160
	global_load_dword v252, v[36:37], off offset:192
	global_load_dword v253, v[36:37], off offset:224
	s_waitcnt vmcnt(0)
	v_mul_f32_e32 v28, v245, v28
	v_mul_f32_e32 v29, v245, v29
	v_mul_f32_e32 v30, v245, v30
	v_mul_f32_e32 v31, v245, v31
	v_mul_f32_e32 v24, v246, v24
	v_mul_f32_e32 v25, v246, v25
	v_mul_f32_e32 v26, v246, v26
	v_mul_f32_e32 v27, v246, v27
	v_mul_f32_e32 v20, v247, v20
	v_mul_f32_e32 v21, v247, v21
	v_mul_f32_e32 v22, v247, v22
	v_mul_f32_e32 v23, v247, v23
	v_mul_f32_e32 v16, v248, v16
	v_mul_f32_e32 v17, v248, v17
	v_mul_f32_e32 v18, v248, v18
	v_mul_f32_e32 v19, v248, v19
	v_mul_f32_e32 v12, v249, v12
	v_mul_f32_e32 v13, v249, v13
	v_mul_f32_e32 v14, v249, v14
	v_mul_f32_e32 v15, v249, v15
	v_mul_f32_e32 v8, v251, v8
	v_mul_f32_e32 v9, v251, v9
	v_mul_f32_e32 v10, v251, v10
	v_mul_f32_e32 v11, v251, v11
	v_mul_f32_e32 v4, v252, v4
	v_mul_f32_e32 v5, v252, v5
	v_mul_f32_e32 v6, v252, v6
	v_mul_f32_e32 v7, v252, v7
	v_mul_f32_e32 v0, v253, v0
	v_mul_f32_e32 v1, v253, v1
	v_mul_f32_e32 v2, v253, v2
	v_mul_f32_e32 v3, v253, v3
	ds_write2_b32 v44, v28, v29 offset1:1
	ds_write2_b32 v44, v30, v31 offset0:2 offset1:3
	v_add_u32_e32 v254, 0x420, v44
	ds_write2_b32 v254, v24, v25 offset1:1
	ds_write2_b32 v254, v26, v27 offset0:2 offset1:3
	v_add_u32_e32 v254, 0x840, v44
	ds_write2_b32 v254, v20, v21 offset1:1
	ds_write2_b32 v254, v22, v23 offset0:2 offset1:3
	v_add_u32_e32 v254, 0xc60, v44
	ds_write2_b32 v254, v16, v17 offset1:1
	ds_write2_b32 v254, v18, v19 offset0:2 offset1:3
	v_add_u32_e32 v254, 0x1080, v44
	ds_write2_b32 v254, v12, v13 offset1:1
	ds_write2_b32 v254, v14, v15 offset0:2 offset1:3
	v_add_u32_e32 v254, 0x14a0, v44
	ds_write2_b32 v254, v8, v9 offset1:1
	ds_write2_b32 v254, v10, v11 offset0:2 offset1:3
	v_add_u32_e32 v254, 0x18c0, v44
	ds_write2_b32 v254, v4, v5 offset1:1
	ds_write2_b32 v254, v6, v7 offset0:2 offset1:3
	v_add_u32_e32 v254, 0x1ce0, v44
	ds_write2_b32 v254, v0, v1 offset1:1
	ds_write2_b32 v254, v2, v3 offset0:2 offset1:3
	s_branch .LBB0_1763

; #define LAS __attribute__((address_space(3)))
; __device__ __forceinline__ unsigned pkbf(float lo, float hi) { const f32x2_m v = {lo, hi}; const bf16x2_m b = __builtin_convertvector(v, bf16x2_m); return __builtin_bit_cast(unsigned, b); }
; __device__ __forceinline__ void tr_item(const float* W, const float* nw, int K, int N, bf16* WT, int k0, int n0, int drow0, LAS float* scr, int lane) {
;     { const int r = lane >> 3, c4 = lane & 7; f32x4 v[8];
; #pragma unroll
;       for (int i = 0; i < 8; ++i) v[i] = *(const f32x4*)(W + (size_t)(k0 + 8 * i + r) * N + n0 + 4 * c4);
; #pragma unroll
;       for (int i = 0; i < 8; ++i) { LAS float* d = scr + (8 * i + r) * 33 + 4 * c4; const float s = nw ? nw[k0 + 8 * i + r] : 1.f; d[0] = v[i].x * s; d[1] = v[i].y * s; d[2] = v[i].z * s; d[3] = v[i].w * s; } }
;     asm volatile("s_waitcnt lgkmcnt(0)" ::: "memory");
;     const int c = lane & 7;
; #pragma unroll
;     for (int j = 0; j < 4; ++j) { const int n = (lane >> 3) + 8 * j; const LAS float* s = scr + (8 * c) * 33 + n;
;         v4u o; o.x = pkbf(s[0 * 33], s[1 * 33]); o.y = pkbf(s[2 * 33], s[3 * 33]); o.z = pkbf(s[4 * 33], s[5 * 33]); o.w = pkbf(s[6 * 33], s[7 * 33]);
;         *(v4u*)(WT + (size_t)(drow0 + n) * K + k0 + 8 * c) = o; }
;     asm volatile("s_waitcnt lgkmcnt(0)" ::: "memory");
; }
; template <int MODE> __device__ __forceinline__ void conv_mat(const float* W, const float* nw, int K, int N, bf16* WT, LAS float* scr, int gw, int NGW, int lane) {
;     const int nblk = N / 32, nitems = (K / 64) * nblk;
;     for (int it = gw; it < nitems; it += NGW) { const int kb = it / nblk, nb = it % nblk, n0 = 32 * nb; int d = n0;
;         if (MODE == 1) { d = (n0 < DFF) ? 256 * (n0 / 128) + (n0 % 128) : 256 * ((n0 - DFF) / 128) + 128 + ((n0 - DFF) % 128); }
;         tr_item(W, nw, K, N, WT, 64 * kb, n0, d, scr, lane); }
.LBB0_1778:
	s_ashr_i32 s0, s5, 31
	s_lshr_b32 s0, s0, 26
	s_add_i32 s0, s5, s0
	s_ashr_i32 s10, s0, 6
	s_andn2_b32 s0, s0, 63
	s_lshl_b32 s1, s10, 11
	v_or_b32_e32 v22, s0, v224
	s_sub_i32 s12, s3, s1
	v_ashrrev_i32_e32 v23, 31, v22
	v_or_b32_e32 v24, 8, v22
	v_or_b32_e32 v26, 16, v22
	v_or_b32_e32 v28, 24, v22
	v_or_b32_e32 v30, 32, v22
	v_or_b32_e32 v32, 40, v22
	v_or_b32_e32 v34, 48, v22
	v_or_b32_e32 v36, 56, v22
	s_ashr_i32 s13, s12, 31
	v_lshlrev_b64 v[22:23], 13, v[22:23]
	v_ashrrev_i32_e32 v25, 31, v24
	v_ashrrev_i32_e32 v27, 31, v26
	v_ashrrev_i32_e32 v29, 31, v28
	v_ashrrev_i32_e32 v31, 31, v30
	v_ashrrev_i32_e32 v33, 31, v32
	v_ashrrev_i32_e32 v35, 31, v34
	v_ashrrev_i32_e32 v37, 31, v36
	v_lshl_add_u64 v[38:39], s[12:13], 2, v[0:1]
	v_lshlrev_b64 v[24:25], 13, v[24:25]
	v_lshlrev_b64 v[26:27], 13, v[26:27]
	v_lshlrev_b64 v[28:29], 13, v[28:29]
	v_lshlrev_b64 v[30:31], 13, v[30:31]
	v_lshlrev_b64 v[32:33], 13, v[32:33]
	v_lshlrev_b64 v[34:35], 13, v[34:35]
	v_lshlrev_b64 v[36:37], 13, v[36:37]
	v_lshl_add_u64 v[54:55], v[38:39], 0, v[22:23]
	v_lshl_add_u64 v[56:57], v[38:39], 0, v[24:25]
	v_lshl_add_u64 v[58:59], v[38:39], 0, v[26:27]
	v_lshl_add_u64 v[60:61], v[38:39], 0, v[28:29]
	v_lshl_add_u64 v[62:63], v[38:39], 0, v[30:31]
	v_lshl_add_u64 v[64:65], v[38:39], 0, v[32:33]
	v_lshl_add_u64 v[66:67], v[38:39], 0, v[34:35]
	v_lshl_add_u64 v[68:69], v[38:39], 0, v[36:37]
	global_load_dwordx4 v[22:25], v[54:55], off nt
	global_load_dwordx4 v[26:29], v[56:57], off nt
	global_load_dwordx4 v[30:33], v[58:59], off nt
	global_load_dwordx4 v[34:37], v[60:61], off nt
	global_load_dwordx4 v[38:41], v[62:63], off nt
	global_load_dwordx4 v[42:45], v[64:65], off nt
	global_load_dwordx4 v[46:49], v[66:67], off nt
	global_load_dwordx4 v[50:53], v[68:69], off nt
	s_mul_i32 s10, s10, 0xff500000
	v_add_u32_e32 v56, s10, v5
	s_ashr_i32 s1, s0, 31
	v_add_u32_e32 v58, 0xb000, v56
	v_add_u32_e32 v60, 0x16000, v56
	v_add_u32_e32 v62, 0x21000, v56
	v_lshl_add_u64 v[54:55], s[0:1], 1, v[2:3]
	v_ashrrev_i32_e32 v57, 31, v56
	v_ashrrev_i32_e32 v59, 31, v58
	v_ashrrev_i32_e32 v61, 31, v60
	v_ashrrev_i32_e32 v63, 31, v62
	v_lshl_add_u64 v[56:57], v[56:57], 1, v[54:55]
	v_lshl_add_u64 v[58:59], v[58:59], 1, v[54:55]
	v_lshl_add_u64 v[60:61], v[60:61], 1, v[54:55]
	v_lshl_add_u64 v[54:55], v[62:63], 1, v[54:55]
	s_add_i32 s5, s5, s64
	s_add_i32 s3, s3, s4
	s_cmpk_lt_i32 s5, 0x1600
	v_add_u32_e32 v5, s11, v5
	s_waitcnt vmcnt(7)
	ds_write2_b32 v6, v22, v23 offset1:1
	ds_write2_b32 v6, v24, v25 offset0:2 offset1:3
	s_waitcnt vmcnt(6)
	ds_write2_b32 v7, v26, v27 offset1:1
	ds_write2_b32 v8, v28, v29 offset1:1
	s_waitcnt vmcnt(5)
	ds_write2_b32 v9, v30, v31 offset1:1
	ds_write2_b32 v10, v32, v33 offset1:1
	s_waitcnt vmcnt(4)
	ds_write2_b32 v11, v34, v35 offset1:1
	ds_write2_b32 v12, v36, v37 offset1:1
	s_waitcnt vmcnt(3)
	ds_write2_b32 v13, v38, v39 offset1:1
	ds_write2_b32 v14, v40, v41 offset1:1
	s_waitcnt vmcnt(2)
	ds_write2_b32 v15, v42, v43 offset1:1
	ds_write2_b32 v16, v44, v45 offset1:1
	s_waitcnt vmcnt(1)
	ds_write2_b32 v17, v46, v47 offset1:1
	ds_write2_b32 v18, v48, v49 offset1:1
	s_waitcnt vmcnt(0)
	ds_write2_b32 v19, v50, v51 offset1:1
	ds_write2_b32 v20, v52, v53 offset1:1
	s_waitcnt lgkmcnt(0)
	ds_read2_b32 v[26:27], v4 offset0:33 offset1:41
	ds_read2_b32 v[28:29], v4 offset1:8
	ds_read2_b32 v[30:31], v4 offset0:66 offset1:74
	ds_read2_b32 v[32:33], v4 offset0:99 offset1:107
	ds_read2_b32 v[34:35], v4 offset0:132 offset1:140
	ds_read2_b32 v[36:37], v4 offset0:165 offset1:173
	ds_read2_b32 v[38:39], v4 offset0:198 offset1:206
	ds_read2_b32 v[40:41], v4 offset0:231 offset1:239
	ds_read2_b32 v[42:43], v4 offset0:49 offset1:57
	ds_read2_b32 v[44:45], v4 offset0:16 offset1:24
	ds_read2_b32 v[46:47], v4 offset0:82 offset1:90
	ds_read2_b32 v[48:49], v4 offset0:115 offset1:123
	ds_read2_b32 v[50:51], v4 offset0:148 offset1:156
	ds_read2_b32 v[52:53], v4 offset0:181 offset1:189
	ds_read2_b32 v[62:63], v4 offset0:214 offset1:222
	ds_read2_b32 v[64:65], v4 offset0:247 offset1:255
	s_waitcnt lgkmcnt(14)
	v_cvt_pk_bf16_f32 v22, v28, v26
	s_waitcnt lgkmcnt(12)
	v_cvt_pk_bf16_f32 v23, v30, v32
	s_waitcnt lgkmcnt(10)
	v_cvt_pk_bf16_f32 v24, v34, v36
	s_waitcnt lgkmcnt(8)
	v_cvt_pk_bf16_f32 v25, v38, v40
	v_cvt_pk_bf16_f32 v26, v29, v27
	v_cvt_pk_bf16_f32 v27, v31, v33
	v_cvt_pk_bf16_f32 v28, v35, v37
	v_cvt_pk_bf16_f32 v29, v39, v41
	s_waitcnt lgkmcnt(6)
	v_cvt_pk_bf16_f32 v30, v44, v42
	s_waitcnt lgkmcnt(4)
	v_cvt_pk_bf16_f32 v31, v46, v48
	s_waitcnt lgkmcnt(2)
	v_cvt_pk_bf16_f32 v32, v50, v52
	s_waitcnt lgkmcnt(0)
	v_cvt_pk_bf16_f32 v33, v62, v64
	v_cvt_pk_bf16_f32 v34, v45, v43
	v_cvt_pk_bf16_f32 v35, v47, v49
	v_cvt_pk_bf16_f32 v36, v51, v53
	v_cvt_pk_bf16_f32 v37, v63, v65
	global_store_dwordx4 v[56:57], v[22:25], off
	global_store_dwordx4 v[58:59], v[26:29], off
	global_store_dwordx4 v[60:61], v[30:33], off
	global_store_dwordx4 v[54:55], v[34:37], off
	s_waitcnt lgkmcnt(0)
	s_cbranch_scc1 .LBB0_1778
